# MLA prompt loop: 3-buffer LDS ring, tile t+2 stored mid-tile, next tile K fragments prefetched before the barrier
# speedup vs baseline: 1.0094x; 1.0094x over previous
.LBB0_950:
	s_or_b64 exec, exec, s[14:15]
	v_bfe_u32 v2, v6, 2, 2
	v_lshl_or_b32 v2, v7, 2, v2
	v_and_b32_e32 v1, 31, v6
	v_mul_u32_u24_e32 v140, 0x150, v2
	v_and_b32_e32 v2, 16, v6
	v_lshlrev_b32_e32 v3, 2, v6
	v_add_u32_e32 v143, v9, v8
	v_and_or_b32 v2, v3, 12, v2
	v_mul_u32_u24_e32 v142, 0x150, v1
	v_mul_lo_u32 v1, v143, 20
	v_add_u32_e32 v146, v12, v11
	v_lshlrev_b32_e32 v141, 1, v2
	v_sub_u32_e32 v1, v6, v1
	v_mul_lo_u32 v2, v146, 20
	v_sub_u32_e32 v4, v10, v2
	v_lshlrev_b32_e32 v2, 3, v1
	v_mov_b32_e32 v3, v193
	v_lshl_add_u64 v[126:127], v[2:3], 1, s[68:69]
	v_ashrrev_i32_e32 v3, 31, v2
	v_lshlrev_b32_e32 v145, 4, v1
	v_cmp_gt_i32_e64 s[14:15], 16, v1
	v_lshl_add_u64 v[128:129], v[2:3], 1, s[66:67]
	v_lshlrev_b32_e32 v2, 3, v4
	v_mov_b32_e32 v3, v193
	v_mov_b32_e32 v1, v193
	v_lshl_add_u64 v[130:131], v[2:3], 1, s[68:69]
	v_ashrrev_i32_e32 v3, 31, v2
	v_lshl_add_u64 v[134:135], v[0:1], 1, s[68:69]
	v_ashrrev_i32_e32 v1, 31, v0
	v_mov_b32_e32 v14, v193
	v_mov_b32_e32 v15, v193
	s_lshl_b32 s4, s19, 2
	s_lshl_b32 s50, s18, 2
	v_lshlrev_b32_e32 v148, 4, v4
	v_lshlrev_b32_e32 v150, 4, v16
	v_cmp_gt_i32_e64 s[16:17], 16, v4
	v_lshl_add_u64 v[132:133], v[2:3], 1, s[66:67]
	v_cmp_gt_i32_e64 s[18:19], 16, v16
	v_lshl_add_u64 v[136:137], v[0:1], 1, s[66:67]
	v_mov_b32_e32 v0, v193
	v_mov_b32_e32 v1, v193
	v_mov_b32_e32 v2, v193
	v_mov_b32_e32 v3, v193
	v_mov_b32_e32 v4, v193
	v_mov_b32_e32 v5, v193
	v_mov_b32_e32 v6, v193
	v_mov_b32_e32 v7, v193
	v_mov_b32_e32 v8, v193
	v_mov_b32_e32 v9, v193
	v_mov_b32_e32 v10, v193
	v_mov_b32_e32 v11, v193
	v_mov_b32_e32 v12, v193
	v_mov_b32_e32 v13, v193
	v_mov_b64_e32 v[30:31], v[14:15]
	s_sub_i32 s47, 64, s4
	s_add_i32 s50, s50, s71
	s_sub_i32 s51, 62, s4
	s_sub_i32 s60, 59, s4
	v_mul_lo_u32 v144, v143, s83
	v_mul_lo_u32 v147, v146, s83
	v_mul_lo_u32 v149, v139, s83
	s_mov_b32 s68, 0
	s_waitcnt vmcnt(14)
	v_mov_b32_e32 v152, 0xf149f2ca
	v_mov_b32_e32 v151, 0
	v_mov_b64_e32 v[28:29], v[12:13]
	v_mov_b64_e32 v[26:27], v[10:11]
	v_mov_b64_e32 v[24:25], v[8:9]
	v_mov_b64_e32 v[22:23], v[6:7]
	v_mov_b64_e32 v[20:21], v[4:5]
	v_mov_b64_e32 v[18:19], v[2:3]
	v_mov_b64_e32 v[16:17], v[0:1]
	s_mov_b32 s69, 0
	s_branch .Lst_entry

.Lst_entry:
	v_add_u32_e32 v216, s68, v143
	v_add_u32_e32 v216, 0x100, v216
	v_ashrrev_i32_e32 v217, 31, v216
	v_lshlrev_b64 v[218:219], 12, v[216:217]
	v_lshlrev_b64 v[216:217], 6, v[216:217]
	v_lshl_add_u64 v[216:217], v[126:127], 0, v[216:217]
	v_lshl_add_u64 v[218:219], v[128:129], 0, v[218:219]
	v_lshl_add_u64 v[216:217], v[216:217], 0, s[64:65]
	v_cndmask_b32_e64 v216, v216, v218, s[14:15]
	v_subrev_u32_e32 v190, s30, v216
	v_mov_b32_e32 v216, 0x1000
	v_mov_b32_e32 v217, 0x40000
	v_cndmask_b32_e64 v197, v216, v217, s[14:15]
	v_add_u32_e32 v216, s68, v146
	v_add_u32_e32 v216, 0x100, v216
	v_ashrrev_i32_e32 v217, 31, v216
	v_lshlrev_b64 v[218:219], 12, v[216:217]
	v_lshlrev_b64 v[216:217], 6, v[216:217]
	v_lshl_add_u64 v[216:217], v[130:131], 0, v[216:217]
	v_lshl_add_u64 v[218:219], v[132:133], 0, v[218:219]
	v_lshl_add_u64 v[216:217], v[216:217], 0, s[64:65]
	v_cndmask_b32_e64 v216, v216, v218, s[16:17]
	v_subrev_u32_e32 v191, s30, v216
	v_mov_b32_e32 v216, 0x1000
	v_mov_b32_e32 v217, 0x40000
	v_cndmask_b32_e64 v208, v216, v217, s[16:17]
	v_add_u32_e32 v216, s68, v139
	v_add_u32_e32 v216, 0x100, v216
	v_ashrrev_i32_e32 v217, 31, v216
	v_lshlrev_b64 v[218:219], 12, v[216:217]
	v_lshlrev_b64 v[216:217], 6, v[216:217]
	v_lshl_add_u64 v[216:217], v[134:135], 0, v[216:217]
	v_lshl_add_u64 v[218:219], v[136:137], 0, v[218:219]
	v_lshl_add_u64 v[216:217], v[216:217], 0, s[64:65]
	v_cndmask_b32_e64 v216, v216, v218, s[18:19]
	v_subrev_u32_e32 v196, s30, v216
	v_mov_b32_e32 v216, 0x1000
	v_mov_b32_e32 v217, 0x40000
	v_cndmask_b32_e64 v209, v216, v217, s[18:19]
	v_mov_b32_e32 v236, 0
	v_mov_b32_e32 v237, 0
	v_mov_b32_e32 v238, 0
	v_mov_b32_e32 v239, 0
	v_mov_b32_e32 v240, 0
	v_mov_b32_e32 v241, 0
	v_mov_b32_e32 v242, 0
	v_mov_b32_e32 v243, 0
	v_mov_b32_e32 v244, 0
	v_mov_b32_e32 v245, 0
	v_mov_b32_e32 v246, 0
	v_mov_b32_e32 v247, 0
	v_mov_b32_e32 v248, 0
	v_mov_b32_e32 v249, 0
	v_mov_b32_e32 v250, 0
	v_mov_b32_e32 v251, 0
	v_add_u32_e32 v194, v192, v142
	v_add_u32_e32 v195, v140, v141
	v_add_u32_e32 v203, v144, v145
	v_add_u32_e32 v252, v147, v148
	v_add_u32_e32 v253, v149, v150
	s_and_saveexec_b64 s[66:67], s[8:9]
	s_cbranch_execz .Lst_pre_s1
	ds_write_b128 v203, v[100:103] offset:21504

.Lst_pre_s3:
	s_or_b64 exec, exec, s[66:67]
	s_cmp_lt_i32 s60, 0
	s_cbranch_scc1 .Lst_pre_nold
	global_load_dwordx4 v[100:103], v190, s[30:31]
	v_add_u32_e32 v190, v197, v190
	global_load_dwordx4 v[104:107], v191, s[30:31]
	v_add_u32_e32 v191, v208, v191
	s_and_saveexec_b64 s[66:67], s[12:13]
	s_cbranch_execz .Lst_pre_l2
	global_load_dwordx4 v[108:111], v196, s[30:31]
	v_add_u32_e32 v196, v209, v196

.Lst_pre_nold:
	s_waitcnt lgkmcnt(0)
	s_barrier
	ds_read_b128 v[220:223], v194
	ds_read_b128 v[224:227], v194 offset:32
	ds_read_b128 v[228:231], v194 offset:64
	ds_read_b128 v[232:235], v194 offset:96
	ds_read_b128 v[126:129], v194 offset:256
	ds_read_b128 v[130:133], v194 offset:288
	ds_read_b128 v[134:137], v194 offset:10752
	ds_read_b128 v[212:215], v194 offset:10784
	ds_read_b128 v[204:207], v194 offset:11008
	ds_read_b128 v[186:189], v194 offset:11040
	ds_read_b128 v[154:157], v194 offset:10816
	ds_read_b128 v[158:161], v194 offset:10848
.Lst_top:
	s_add_i32 s93, s69, 0
	s_cmp_gt_i32 s93, s50
	s_cbranch_scc1 .Lst_skip0
	s_waitcnt lgkmcnt(2)
	v_mfma_f32_32x32x16_bf16 v[48:63], v[220:223], v[64:67], v[236:251]
	v_mfma_f32_32x32x16_bf16 v[48:63], v[224:227], v[68:71], v[48:63]
	v_mfma_f32_32x32x16_bf16 v[48:63], v[228:231], v[72:75], v[48:63]
	v_mfma_f32_32x32x16_bf16 v[48:63], v[232:235], v[76:79], v[48:63]
	v_mfma_f32_32x32x16_bf16 v[48:63], v[126:129], v[80:83], v[48:63]
	v_mfma_f32_32x32x16_bf16 v[48:63], v[130:133], v[84:87], v[48:63]
	v_mfma_f32_32x32x16_bf16 v[32:47], v[134:137], v[64:67], v[236:251]
	v_mfma_f32_32x32x16_bf16 v[32:47], v[212:215], v[68:71], v[32:47]
	s_waitcnt lgkmcnt(1)
	v_mfma_f32_32x32x16_bf16 v[32:47], v[154:157], v[72:75], v[32:47]
	s_waitcnt lgkmcnt(0)
	v_mfma_f32_32x32x16_bf16 v[32:47], v[158:161], v[76:79], v[32:47]
	v_mfma_f32_32x32x16_bf16 v[32:47], v[204:207], v[80:83], v[32:47]
	v_mfma_f32_32x32x16_bf16 v[32:47], v[186:189], v[84:87], v[32:47]
	s_cmp_ge_i32 s93, s51
	s_cbranch_scc1 .Lst_a0_nost
	s_cmp_eq_u32 s93, 0
	s_cbranch_scc1 .Lst_a0_nw
	s_waitcnt vmcnt(0)
.Lst_a0_nw:
	s_and_saveexec_b64 s[66:67], s[8:9]
	s_cbranch_execz .Lst_a0_s1
	ds_write_b128 v203, v[112:115] offset:43008
.Lst_a0_s1:
	s_or_b64 exec, exec, s[66:67]
	s_and_saveexec_b64 s[66:67], s[10:11]
	s_cbranch_execz .Lst_a0_s2
	ds_write_b128 v252, v[116:119] offset:43008
.Lst_a0_s2:
	s_or_b64 exec, exec, s[66:67]
	s_and_saveexec_b64 s[66:67], s[12:13]
	s_cbranch_execz .Lst_a0_s3
	ds_write_b128 v253, v[120:123] offset:43008

.Lst_a0_nost:
	s_cmp_ge_i32 s93, s60
	s_cbranch_scc1 .Lst_a0_nold
	global_load_dwordx4 v[112:115], v190, s[30:31]
	v_add_u32_e32 v190, v197, v190
	global_load_dwordx4 v[116:119], v191, s[30:31]
	v_add_u32_e32 v191, v208, v191
	s_and_saveexec_b64 s[66:67], s[12:13]
	s_cbranch_execz .Lst_a0_l2
	global_load_dwordx4 v[120:123], v196, s[30:31]
	v_add_u32_e32 v196, v209, v196

.Lst_a0_nold:
	ds_read_b128 v[220:223], v194 offset:21504
	ds_read_b128 v[224:227], v194 offset:21536
	ds_read_b128 v[228:231], v194 offset:21568
	ds_read_b128 v[232:235], v194 offset:21600
	ds_read_b128 v[126:129], v194 offset:21760
	ds_read_b128 v[130:133], v194 offset:21792
	ds_read_b128 v[134:137], v194 offset:32256
	ds_read_b128 v[212:215], v194 offset:32288
	ds_read_b128 v[204:207], v194 offset:32512
	ds_read_b128 v[186:189], v194 offset:32544
	v_max_f32_e32 v162, v48, v48
	v_max_f32_e32 v153, v49, v49
	v_max_f32_e32 v153, v162, v153
	v_max3_f32 v153, v153, v50, v51
	v_max3_f32 v153, v153, v52, v53
	v_max3_f32 v153, v153, v54, v55
	v_max3_f32 v153, v153, v56, v57
	v_max3_f32 v153, v153, v58, v59
	v_max3_f32 v153, v153, v60, v61
	v_max3_f32 v153, v153, v62, v63
	s_nop 1
	v_max3_f32 v153, v153, v32, v33
	v_max3_f32 v153, v153, v34, v35
	v_max3_f32 v153, v153, v36, v37
	v_max3_f32 v153, v153, v38, v39
	v_max3_f32 v153, v153, v40, v41
	v_max3_f32 v153, v153, v42, v43
	v_max3_f32 v153, v153, v44, v45
	v_max3_f32 v153, v153, v46, v47
	s_cmp_eq_u32 s93, 0
	s_cbranch_scc1 .Lst_first
	v_cmp_lt_f32_e32 vcc, 0x41000000, v153
	s_cbranch_vccz .Lst_norescale_0
	v_mov_b32_e32 v154, v153
	s_nop 1
	v_permlane32_swap_b32_e32 v153, v154
	v_max_f32_e32 v153, v153, v154
	v_max_f32_e32 v154, 0, v153
	v_exp_f32_e64 v152, -v154
	v_sub_f32_e32 v236, v236, v154
	v_sub_f32_e32 v237, v237, v154
	v_sub_f32_e32 v238, v238, v154
	v_sub_f32_e32 v239, v239, v154
	v_sub_f32_e32 v240, v240, v154
	v_sub_f32_e32 v241, v241, v154
	v_sub_f32_e32 v242, v242, v154
	v_sub_f32_e32 v243, v243, v154
	v_sub_f32_e32 v244, v244, v154
	v_sub_f32_e32 v245, v245, v154
	v_sub_f32_e32 v246, v246, v154
	v_sub_f32_e32 v247, v247, v154
	v_sub_f32_e32 v248, v248, v154
	v_sub_f32_e32 v249, v249, v154
	v_sub_f32_e32 v250, v250, v154
	v_sub_f32_e32 v251, v251, v154
	v_pk_mul_f32 v[30:31], v[30:31], v[152:153] op_sel_hi:[1,0]
	v_pk_mul_f32 v[28:29], v[28:29], v[152:153] op_sel_hi:[1,0]
	v_pk_mul_f32 v[26:27], v[26:27], v[152:153] op_sel_hi:[1,0]
	v_pk_mul_f32 v[24:25], v[24:25], v[152:153] op_sel_hi:[1,0]
	v_pk_mul_f32 v[22:23], v[22:23], v[152:153] op_sel_hi:[1,0]
	v_pk_mul_f32 v[20:21], v[20:21], v[152:153] op_sel_hi:[1,0]
	v_pk_mul_f32 v[18:19], v[18:19], v[152:153] op_sel_hi:[1,0]
	v_pk_mul_f32 v[16:17], v[16:17], v[152:153] op_sel_hi:[1,0]
	v_pk_mul_f32 v[14:15], v[14:15], v[152:153] op_sel_hi:[1,0]
	v_pk_mul_f32 v[12:13], v[12:13], v[152:153] op_sel_hi:[1,0]
	v_pk_mul_f32 v[10:11], v[10:11], v[152:153] op_sel_hi:[1,0]
	v_pk_mul_f32 v[8:9], v[8:9], v[152:153] op_sel_hi:[1,0]
	v_pk_mul_f32 v[6:7], v[6:7], v[152:153] op_sel_hi:[1,0]
	v_pk_mul_f32 v[4:5], v[4:5], v[152:153] op_sel_hi:[1,0]
	v_pk_mul_f32 v[2:3], v[2:3], v[152:153] op_sel_hi:[1,0]
	v_pk_mul_f32 v[0:1], v[0:1], v[152:153] op_sel_hi:[1,0]
	v_mul_f32_e32 v151, v151, v152

.Lst_norescale_0:
	v_exp_f32_e32 v170, v32
	v_exp_f32_e32 v171, v33
	v_exp_f32_e32 v172, v34
	v_exp_f32_e32 v173, v35
	v_exp_f32_e32 v174, v36
	v_exp_f32_e32 v175, v37
	v_exp_f32_e32 v176, v38
	v_exp_f32_e32 v158, v52
	v_exp_f32_e32 v177, v39
	v_exp_f32_e32 v159, v53
	v_exp_f32_e32 v178, v40
	v_exp_f32_e32 v160, v54
	v_exp_f32_e32 v179, v41
	v_exp_f32_e32 v48, v48
	v_exp_f32_e32 v49, v49
	v_exp_f32_e32 v50, v50
	v_exp_f32_e32 v51, v51
	v_exp_f32_e32 v161, v55
	v_exp_f32_e32 v180, v42
	v_exp_f32_e32 v162, v56
	v_exp_f32_e32 v181, v43
	ds_read_b64_tr_b16 v[36:37], v195 offset:128
	ds_read_b64_tr_b16 v[38:39], v195 offset:2816
	v_exp_f32_e32 v163, v57
	v_exp_f32_e32 v182, v44
	v_exp_f32_e32 v164, v58
	v_exp_f32_e32 v183, v45
	v_exp_f32_e32 v165, v59
	v_exp_f32_e32 v184, v46
	v_exp_f32_e32 v166, v60
	v_cvt_pk_bf16_f32 v32, v48, v49
	v_cvt_pk_bf16_f32 v33, v50, v51
	v_cvt_pk_bf16_f32 v34, v158, v159
	v_cvt_pk_bf16_f32 v35, v160, v161
	v_exp_f32_e32 v167, v61
	s_waitcnt lgkmcnt(0)
	v_mfma_f32_32x32x16_bf16 v[16:31], v[36:39], v[32:35], v[16:31]
	v_exp_f32_e32 v168, v62
	v_exp_f32_e32 v169, v63
	v_add_f32_e32 v153, v49, v48
	v_add_f32_e32 v153, v50, v153
	v_add_f32_e32 v153, v51, v153
	v_exp_f32_e32 v185, v47
	ds_read_b64_tr_b16 v[44:45], v195 offset:5504
	ds_read_b64_tr_b16 v[46:47], v195 offset:8192
	ds_read_b64_tr_b16 v[50:51], v195 offset:2880
	ds_read_b64_tr_b16 v[48:49], v195 offset:192
	v_cvt_pk_bf16_f32 v40, v162, v163
	v_cvt_pk_bf16_f32 v41, v164, v165
	v_cvt_pk_bf16_f32 v42, v166, v167
	v_cvt_pk_bf16_f32 v43, v168, v169
	ds_read_b64_tr_b16 v[52:53], v195 offset:10880
	ds_read_b64_tr_b16 v[54:55], v195 offset:13568
	ds_read_b64_tr_b16 v[58:59], v195 offset:8256
	ds_read_b64_tr_b16 v[56:57], v195 offset:5568
	s_waitcnt lgkmcnt(6)
	v_mfma_f32_32x32x16_bf16 v[16:31], v[44:47], v[40:43], v[16:31]
	v_cvt_pk_bf16_f32 v36, v170, v171
	v_cvt_pk_bf16_f32 v37, v172, v173
	v_cvt_pk_bf16_f32 v38, v174, v175
	v_cvt_pk_bf16_f32 v39, v176, v177
	ds_read_b64_tr_b16 v[44:45], v195 offset:16256
	ds_read_b64_tr_b16 v[46:47], v195 offset:18944
	ds_read_b64_tr_b16 v[62:63], v195 offset:13632
	ds_read_b64_tr_b16 v[60:61], v195 offset:10944
	ds_read_b64_tr_b16 v[156:157], v195 offset:19008
	ds_read_b64_tr_b16 v[154:155], v195 offset:16320
	s_waitcnt lgkmcnt(8)
	v_mfma_f32_32x32x16_bf16 v[16:31], v[52:55], v[36:39], v[16:31]
	v_cvt_pk_bf16_f32 v52, v178, v179
	v_cvt_pk_bf16_f32 v53, v180, v181
	v_cvt_pk_bf16_f32 v54, v182, v183
	v_cvt_pk_bf16_f32 v55, v184, v185
	v_mfma_f32_32x32x16_bf16 v[0:15], v[48:51], v[32:35], v[0:15]
	s_waitcnt lgkmcnt(4)
	v_mfma_f32_32x32x16_bf16 v[16:31], v[44:47], v[52:55], v[16:31]
	v_add_f32_e32 v44, v158, v153
	v_add_f32_e32 v44, v159, v44
	v_add_f32_e32 v44, v160, v44
	v_add_f32_e32 v44, v161, v44
	v_add_f32_e32 v44, v162, v44
	v_add_f32_e32 v44, v163, v44
	v_add_f32_e32 v44, v164, v44
	v_mfma_f32_32x32x16_bf16 v[0:15], v[56:59], v[40:43], v[0:15]
	v_add_f32_e32 v32, v165, v44
	v_add_f32_e32 v32, v166, v32
	v_add_f32_e32 v32, v167, v32
	v_add_f32_e32 v32, v168, v32
	v_add_f32_e32 v32, v169, v32
	v_add_f32_e32 v32, v170, v32
	v_add_f32_e32 v32, v171, v32
	s_waitcnt lgkmcnt(2)
	v_mfma_f32_32x32x16_bf16 v[0:15], v[60:63], v[36:39], v[0:15]
	v_add_f32_e32 v32, v172, v32
	v_add_f32_e32 v32, v173, v32
	v_add_f32_e32 v32, v174, v32
	v_add_f32_e32 v32, v175, v32
	v_add_f32_e32 v32, v176, v32
	v_add_f32_e32 v32, v177, v32
	v_add_f32_e32 v32, v178, v32
	v_add_f32_e32 v32, v179, v32
	s_waitcnt lgkmcnt(0)
	v_mfma_f32_32x32x16_bf16 v[0:15], v[154:157], v[52:55], v[0:15]
	v_add_f32_e32 v32, v180, v32
	v_add_f32_e32 v32, v181, v32
	v_add_f32_e32 v32, v182, v32
	v_add_f32_e32 v32, v183, v32
	v_add_f32_e32 v32, v184, v32
	v_add_f32_e32 v32, v185, v32
	v_add_f32_e32 v151, v151, v32
	ds_read_b128 v[154:157], v194 offset:32320
	ds_read_b128 v[158:161], v194 offset:32352
	s_branch .Lst_bar0
.Lst_skip0:
	s_cmp_ge_i32 s93, s51
	s_cbranch_scc1 .Lst_b0_nost
	s_cmp_eq_u32 s93, 0
	s_cbranch_scc1 .Lst_b0_nw
	s_waitcnt vmcnt(0)

.Lst_b0_l2:
	s_or_b64 exec, exec, s[66:67]
.Lst_b0_nold:
	s_waitcnt lgkmcnt(0)
.Lst_bar0:
	s_barrier
	s_add_i32 s93, s69, 1
	s_cmp_ge_u32 s93, s47
	s_cbranch_scc1 .Lst_exit
	s_cmp_gt_i32 s93, s50
	s_cbranch_scc1 .Lst_skip1
	s_waitcnt lgkmcnt(2)
	v_mfma_f32_32x32x16_bf16 v[48:63], v[220:223], v[64:67], v[236:251]
	v_mfma_f32_32x32x16_bf16 v[48:63], v[224:227], v[68:71], v[48:63]
	v_mfma_f32_32x32x16_bf16 v[48:63], v[228:231], v[72:75], v[48:63]
	v_mfma_f32_32x32x16_bf16 v[48:63], v[232:235], v[76:79], v[48:63]
	v_mfma_f32_32x32x16_bf16 v[48:63], v[126:129], v[80:83], v[48:63]
	v_mfma_f32_32x32x16_bf16 v[48:63], v[130:133], v[84:87], v[48:63]
	v_mfma_f32_32x32x16_bf16 v[32:47], v[134:137], v[64:67], v[236:251]
	v_mfma_f32_32x32x16_bf16 v[32:47], v[212:215], v[68:71], v[32:47]
	s_waitcnt lgkmcnt(1)
	v_mfma_f32_32x32x16_bf16 v[32:47], v[154:157], v[72:75], v[32:47]
	s_waitcnt lgkmcnt(0)
	v_mfma_f32_32x32x16_bf16 v[32:47], v[158:161], v[76:79], v[32:47]
	v_mfma_f32_32x32x16_bf16 v[32:47], v[204:207], v[80:83], v[32:47]
	v_mfma_f32_32x32x16_bf16 v[32:47], v[186:189], v[84:87], v[32:47]
	s_cmp_ge_i32 s93, s51
	s_cbranch_scc1 .Lst_a1_nost
	s_waitcnt vmcnt(0)
	s_and_saveexec_b64 s[66:67], s[8:9]
	s_cbranch_execz .Lst_a1_s1
	ds_write_b128 v203, v[88:91]

.Lst_a1_nost:
	s_cmp_ge_i32 s93, s60
	s_cbranch_scc1 .Lst_a1_nold
	global_load_dwordx4 v[88:91], v190, s[30:31]
	v_add_u32_e32 v190, v197, v190
	global_load_dwordx4 v[92:95], v191, s[30:31]
	v_add_u32_e32 v191, v208, v191
	s_and_saveexec_b64 s[66:67], s[12:13]
	s_cbranch_execz .Lst_a1_l2
	global_load_dwordx4 v[96:99], v196, s[30:31]
	v_add_u32_e32 v196, v209, v196

.Lst_a1_nold:
	ds_read_b128 v[220:223], v194 offset:43008
	ds_read_b128 v[224:227], v194 offset:43040
	ds_read_b128 v[228:231], v194 offset:43072
	ds_read_b128 v[232:235], v194 offset:43104
	ds_read_b128 v[126:129], v194 offset:43264
	ds_read_b128 v[130:133], v194 offset:43296
	ds_read_b128 v[134:137], v194 offset:53760
	ds_read_b128 v[212:215], v194 offset:53792
	ds_read_b128 v[204:207], v194 offset:54016
	ds_read_b128 v[186:189], v194 offset:54048
	v_max_f32_e32 v162, v48, v48
	v_max_f32_e32 v153, v49, v49
	v_max_f32_e32 v153, v162, v153
	v_max3_f32 v153, v153, v50, v51
	v_max3_f32 v153, v153, v52, v53
	v_max3_f32 v153, v153, v54, v55
	v_max3_f32 v153, v153, v56, v57
	v_max3_f32 v153, v153, v58, v59
	v_max3_f32 v153, v153, v60, v61
	v_max3_f32 v153, v153, v62, v63
	s_nop 1
	v_max3_f32 v153, v153, v32, v33
	v_max3_f32 v153, v153, v34, v35
	v_max3_f32 v153, v153, v36, v37
	v_max3_f32 v153, v153, v38, v39
	v_max3_f32 v153, v153, v40, v41
	v_max3_f32 v153, v153, v42, v43
	v_max3_f32 v153, v153, v44, v45
	v_max3_f32 v153, v153, v46, v47
	v_cmp_lt_f32_e32 vcc, 0x41000000, v153
	s_cbranch_vccz .Lst_norescale_1
	v_mov_b32_e32 v154, v153
	s_nop 1
	v_permlane32_swap_b32_e32 v153, v154
	v_max_f32_e32 v153, v153, v154
	v_max_f32_e32 v154, 0, v153
	v_exp_f32_e64 v152, -v154
	v_sub_f32_e32 v236, v236, v154
	v_sub_f32_e32 v237, v237, v154
	v_sub_f32_e32 v238, v238, v154
	v_sub_f32_e32 v239, v239, v154
	v_sub_f32_e32 v240, v240, v154
	v_sub_f32_e32 v241, v241, v154
	v_sub_f32_e32 v242, v242, v154
	v_sub_f32_e32 v243, v243, v154
	v_sub_f32_e32 v244, v244, v154
	v_sub_f32_e32 v245, v245, v154
	v_sub_f32_e32 v246, v246, v154
	v_sub_f32_e32 v247, v247, v154
	v_sub_f32_e32 v248, v248, v154
	v_sub_f32_e32 v249, v249, v154
	v_sub_f32_e32 v250, v250, v154
	v_sub_f32_e32 v251, v251, v154
	v_pk_mul_f32 v[30:31], v[30:31], v[152:153] op_sel_hi:[1,0]
	v_pk_mul_f32 v[28:29], v[28:29], v[152:153] op_sel_hi:[1,0]
	v_pk_mul_f32 v[26:27], v[26:27], v[152:153] op_sel_hi:[1,0]
	v_pk_mul_f32 v[24:25], v[24:25], v[152:153] op_sel_hi:[1,0]
	v_pk_mul_f32 v[22:23], v[22:23], v[152:153] op_sel_hi:[1,0]
	v_pk_mul_f32 v[20:21], v[20:21], v[152:153] op_sel_hi:[1,0]
	v_pk_mul_f32 v[18:19], v[18:19], v[152:153] op_sel_hi:[1,0]
	v_pk_mul_f32 v[16:17], v[16:17], v[152:153] op_sel_hi:[1,0]
	v_pk_mul_f32 v[14:15], v[14:15], v[152:153] op_sel_hi:[1,0]
	v_pk_mul_f32 v[12:13], v[12:13], v[152:153] op_sel_hi:[1,0]
	v_pk_mul_f32 v[10:11], v[10:11], v[152:153] op_sel_hi:[1,0]
	v_pk_mul_f32 v[8:9], v[8:9], v[152:153] op_sel_hi:[1,0]
	v_pk_mul_f32 v[6:7], v[6:7], v[152:153] op_sel_hi:[1,0]
	v_pk_mul_f32 v[4:5], v[4:5], v[152:153] op_sel_hi:[1,0]
	v_pk_mul_f32 v[2:3], v[2:3], v[152:153] op_sel_hi:[1,0]
	v_pk_mul_f32 v[0:1], v[0:1], v[152:153] op_sel_hi:[1,0]
	v_mul_f32_e32 v151, v151, v152

.Lst_norescale_1:
	v_exp_f32_e32 v170, v32
	v_exp_f32_e32 v171, v33
	v_exp_f32_e32 v172, v34
	v_exp_f32_e32 v173, v35
	v_exp_f32_e32 v174, v36
	v_exp_f32_e32 v175, v37
	v_exp_f32_e32 v176, v38
	v_exp_f32_e32 v158, v52
	v_exp_f32_e32 v177, v39
	v_exp_f32_e32 v159, v53
	v_exp_f32_e32 v178, v40
	v_exp_f32_e32 v160, v54
	v_exp_f32_e32 v179, v41
	v_exp_f32_e32 v48, v48
	v_exp_f32_e32 v49, v49
	v_exp_f32_e32 v50, v50
	v_exp_f32_e32 v51, v51
	v_exp_f32_e32 v161, v55
	v_exp_f32_e32 v180, v42
	v_exp_f32_e32 v162, v56
	v_exp_f32_e32 v181, v43
	ds_read_b64_tr_b16 v[36:37], v195 offset:21632
	ds_read_b64_tr_b16 v[38:39], v195 offset:24320
	v_exp_f32_e32 v163, v57
	v_exp_f32_e32 v182, v44
	v_exp_f32_e32 v164, v58
	v_exp_f32_e32 v183, v45
	v_exp_f32_e32 v165, v59
	v_exp_f32_e32 v184, v46
	v_exp_f32_e32 v166, v60
	v_cvt_pk_bf16_f32 v32, v48, v49
	v_cvt_pk_bf16_f32 v33, v50, v51
	v_cvt_pk_bf16_f32 v34, v158, v159
	v_cvt_pk_bf16_f32 v35, v160, v161
	v_exp_f32_e32 v167, v61
	s_waitcnt lgkmcnt(0)
	v_mfma_f32_32x32x16_bf16 v[16:31], v[36:39], v[32:35], v[16:31]
	v_exp_f32_e32 v168, v62
	v_exp_f32_e32 v169, v63
	v_add_f32_e32 v153, v49, v48
	v_add_f32_e32 v153, v50, v153
	v_add_f32_e32 v153, v51, v153
	v_exp_f32_e32 v185, v47
	ds_read_b64_tr_b16 v[44:45], v195 offset:27008
	ds_read_b64_tr_b16 v[46:47], v195 offset:29696
	ds_read_b64_tr_b16 v[50:51], v195 offset:24384
	ds_read_b64_tr_b16 v[48:49], v195 offset:21696
	v_cvt_pk_bf16_f32 v40, v162, v163
	v_cvt_pk_bf16_f32 v41, v164, v165
	v_cvt_pk_bf16_f32 v42, v166, v167
	v_cvt_pk_bf16_f32 v43, v168, v169
	ds_read_b64_tr_b16 v[52:53], v195 offset:32384
	ds_read_b64_tr_b16 v[54:55], v195 offset:35072
	ds_read_b64_tr_b16 v[58:59], v195 offset:29760
	ds_read_b64_tr_b16 v[56:57], v195 offset:27072
	s_waitcnt lgkmcnt(6)
	v_mfma_f32_32x32x16_bf16 v[16:31], v[44:47], v[40:43], v[16:31]
	v_cvt_pk_bf16_f32 v36, v170, v171
	v_cvt_pk_bf16_f32 v37, v172, v173
	v_cvt_pk_bf16_f32 v38, v174, v175
	v_cvt_pk_bf16_f32 v39, v176, v177
	ds_read_b64_tr_b16 v[44:45], v195 offset:37760
	ds_read_b64_tr_b16 v[46:47], v195 offset:40448
	ds_read_b64_tr_b16 v[62:63], v195 offset:35136
	ds_read_b64_tr_b16 v[60:61], v195 offset:32448
	ds_read_b64_tr_b16 v[156:157], v195 offset:40512
	ds_read_b64_tr_b16 v[154:155], v195 offset:37824
	s_waitcnt lgkmcnt(8)
	v_mfma_f32_32x32x16_bf16 v[16:31], v[52:55], v[36:39], v[16:31]
	v_cvt_pk_bf16_f32 v52, v178, v179
	v_cvt_pk_bf16_f32 v53, v180, v181
	v_cvt_pk_bf16_f32 v54, v182, v183
	v_cvt_pk_bf16_f32 v55, v184, v185
	v_mfma_f32_32x32x16_bf16 v[0:15], v[48:51], v[32:35], v[0:15]
	s_waitcnt lgkmcnt(4)
	v_mfma_f32_32x32x16_bf16 v[16:31], v[44:47], v[52:55], v[16:31]
	v_add_f32_e32 v44, v158, v153
	v_add_f32_e32 v44, v159, v44
	v_add_f32_e32 v44, v160, v44
	v_add_f32_e32 v44, v161, v44
	v_add_f32_e32 v44, v162, v44
	v_add_f32_e32 v44, v163, v44
	v_add_f32_e32 v44, v164, v44
	v_mfma_f32_32x32x16_bf16 v[0:15], v[56:59], v[40:43], v[0:15]
	v_add_f32_e32 v32, v165, v44
	v_add_f32_e32 v32, v166, v32
	v_add_f32_e32 v32, v167, v32
	v_add_f32_e32 v32, v168, v32
	v_add_f32_e32 v32, v169, v32
	v_add_f32_e32 v32, v170, v32
	v_add_f32_e32 v32, v171, v32
	s_waitcnt lgkmcnt(2)
	v_mfma_f32_32x32x16_bf16 v[0:15], v[60:63], v[36:39], v[0:15]
	v_add_f32_e32 v32, v172, v32
	v_add_f32_e32 v32, v173, v32
	v_add_f32_e32 v32, v174, v32
	v_add_f32_e32 v32, v175, v32
	v_add_f32_e32 v32, v176, v32
	v_add_f32_e32 v32, v177, v32
	v_add_f32_e32 v32, v178, v32
	v_add_f32_e32 v32, v179, v32
	s_waitcnt lgkmcnt(0)
	v_mfma_f32_32x32x16_bf16 v[0:15], v[154:157], v[52:55], v[0:15]
	v_add_f32_e32 v32, v180, v32
	v_add_f32_e32 v32, v181, v32
	v_add_f32_e32 v32, v182, v32
	v_add_f32_e32 v32, v183, v32
	v_add_f32_e32 v32, v184, v32
	v_add_f32_e32 v32, v185, v32
	v_add_f32_e32 v151, v151, v32
	ds_read_b128 v[154:157], v194 offset:53824
	ds_read_b128 v[158:161], v194 offset:53856
	s_branch .Lst_bar1
.Lst_skip1:
	s_cmp_ge_i32 s93, s51
	s_cbranch_scc1 .Lst_b1_nost
	s_waitcnt vmcnt(0)
	s_and_saveexec_b64 s[66:67], s[8:9]
	s_cbranch_execz .Lst_b1_s1
	ds_write_b128 v203, v[88:91]

.Lst_b1_l2:
	s_or_b64 exec, exec, s[66:67]
.Lst_b1_nold:
	s_waitcnt lgkmcnt(0)
.Lst_bar1:
	s_barrier
	s_add_i32 s93, s69, 2
	s_cmp_ge_u32 s93, s47
	s_cbranch_scc1 .Lst_exit
	s_cmp_gt_i32 s93, s50
	s_cbranch_scc1 .Lst_skip2
	s_waitcnt lgkmcnt(2)
	v_mfma_f32_32x32x16_bf16 v[48:63], v[220:223], v[64:67], v[236:251]
	v_mfma_f32_32x32x16_bf16 v[48:63], v[224:227], v[68:71], v[48:63]
	v_mfma_f32_32x32x16_bf16 v[48:63], v[228:231], v[72:75], v[48:63]
	v_mfma_f32_32x32x16_bf16 v[48:63], v[232:235], v[76:79], v[48:63]
	v_mfma_f32_32x32x16_bf16 v[48:63], v[126:129], v[80:83], v[48:63]
	v_mfma_f32_32x32x16_bf16 v[48:63], v[130:133], v[84:87], v[48:63]
	v_mfma_f32_32x32x16_bf16 v[32:47], v[134:137], v[64:67], v[236:251]
	v_mfma_f32_32x32x16_bf16 v[32:47], v[212:215], v[68:71], v[32:47]
	s_waitcnt lgkmcnt(1)
	v_mfma_f32_32x32x16_bf16 v[32:47], v[154:157], v[72:75], v[32:47]
	s_waitcnt lgkmcnt(0)
	v_mfma_f32_32x32x16_bf16 v[32:47], v[158:161], v[76:79], v[32:47]
	v_mfma_f32_32x32x16_bf16 v[32:47], v[204:207], v[80:83], v[32:47]
	v_mfma_f32_32x32x16_bf16 v[32:47], v[186:189], v[84:87], v[32:47]
	s_cmp_ge_i32 s93, s51
	s_cbranch_scc1 .Lst_a2_nost
	s_waitcnt vmcnt(0)
	s_and_saveexec_b64 s[66:67], s[8:9]
	s_cbranch_execz .Lst_a2_s1
	ds_write_b128 v203, v[100:103] offset:21504

.Lst_a2_nost:
	s_cmp_ge_i32 s93, s60
	s_cbranch_scc1 .Lst_a2_nold
	global_load_dwordx4 v[100:103], v190, s[30:31]
	v_add_u32_e32 v190, v197, v190
	global_load_dwordx4 v[104:107], v191, s[30:31]
	v_add_u32_e32 v191, v208, v191
	s_and_saveexec_b64 s[66:67], s[12:13]
	s_cbranch_execz .Lst_a2_l2
	global_load_dwordx4 v[108:111], v196, s[30:31]
	v_add_u32_e32 v196, v209, v196

.Lst_a2_nold:
	ds_read_b128 v[220:223], v194
	ds_read_b128 v[224:227], v194 offset:32
	ds_read_b128 v[228:231], v194 offset:64
	ds_read_b128 v[232:235], v194 offset:96
	ds_read_b128 v[126:129], v194 offset:256
	ds_read_b128 v[130:133], v194 offset:288
	ds_read_b128 v[134:137], v194 offset:10752
	ds_read_b128 v[212:215], v194 offset:10784
	ds_read_b128 v[204:207], v194 offset:11008
	ds_read_b128 v[186:189], v194 offset:11040
	v_max_f32_e32 v162, v48, v48
	v_max_f32_e32 v153, v49, v49
	v_max_f32_e32 v153, v162, v153
	v_max3_f32 v153, v153, v50, v51
	v_max3_f32 v153, v153, v52, v53
	v_max3_f32 v153, v153, v54, v55
	v_max3_f32 v153, v153, v56, v57
	v_max3_f32 v153, v153, v58, v59
	v_max3_f32 v153, v153, v60, v61
	v_max3_f32 v153, v153, v62, v63
	s_nop 1
	v_max3_f32 v153, v153, v32, v33
	v_max3_f32 v153, v153, v34, v35
	v_max3_f32 v153, v153, v36, v37
	v_max3_f32 v153, v153, v38, v39
	v_max3_f32 v153, v153, v40, v41
	v_max3_f32 v153, v153, v42, v43
	v_max3_f32 v153, v153, v44, v45
	v_max3_f32 v153, v153, v46, v47
	v_cmp_lt_f32_e32 vcc, 0x41000000, v153
	s_cbranch_vccz .Lst_norescale_2
	v_mov_b32_e32 v154, v153
	s_nop 1
	v_permlane32_swap_b32_e32 v153, v154
	v_max_f32_e32 v153, v153, v154
	v_max_f32_e32 v154, 0, v153
	v_exp_f32_e64 v152, -v154
	v_sub_f32_e32 v236, v236, v154
	v_sub_f32_e32 v237, v237, v154
	v_sub_f32_e32 v238, v238, v154
	v_sub_f32_e32 v239, v239, v154
	v_sub_f32_e32 v240, v240, v154
	v_sub_f32_e32 v241, v241, v154
	v_sub_f32_e32 v242, v242, v154
	v_sub_f32_e32 v243, v243, v154
	v_sub_f32_e32 v244, v244, v154
	v_sub_f32_e32 v245, v245, v154
	v_sub_f32_e32 v246, v246, v154
	v_sub_f32_e32 v247, v247, v154
	v_sub_f32_e32 v248, v248, v154
	v_sub_f32_e32 v249, v249, v154
	v_sub_f32_e32 v250, v250, v154
	v_sub_f32_e32 v251, v251, v154
	v_pk_mul_f32 v[30:31], v[30:31], v[152:153] op_sel_hi:[1,0]
	v_pk_mul_f32 v[28:29], v[28:29], v[152:153] op_sel_hi:[1,0]
	v_pk_mul_f32 v[26:27], v[26:27], v[152:153] op_sel_hi:[1,0]
	v_pk_mul_f32 v[24:25], v[24:25], v[152:153] op_sel_hi:[1,0]
	v_pk_mul_f32 v[22:23], v[22:23], v[152:153] op_sel_hi:[1,0]
	v_pk_mul_f32 v[20:21], v[20:21], v[152:153] op_sel_hi:[1,0]
	v_pk_mul_f32 v[18:19], v[18:19], v[152:153] op_sel_hi:[1,0]
	v_pk_mul_f32 v[16:17], v[16:17], v[152:153] op_sel_hi:[1,0]
	v_pk_mul_f32 v[14:15], v[14:15], v[152:153] op_sel_hi:[1,0]
	v_pk_mul_f32 v[12:13], v[12:13], v[152:153] op_sel_hi:[1,0]
	v_pk_mul_f32 v[10:11], v[10:11], v[152:153] op_sel_hi:[1,0]
	v_pk_mul_f32 v[8:9], v[8:9], v[152:153] op_sel_hi:[1,0]
	v_pk_mul_f32 v[6:7], v[6:7], v[152:153] op_sel_hi:[1,0]
	v_pk_mul_f32 v[4:5], v[4:5], v[152:153] op_sel_hi:[1,0]
	v_pk_mul_f32 v[2:3], v[2:3], v[152:153] op_sel_hi:[1,0]
	v_pk_mul_f32 v[0:1], v[0:1], v[152:153] op_sel_hi:[1,0]
	v_mul_f32_e32 v151, v151, v152

.Lst_norescale_2:
	v_exp_f32_e32 v170, v32
	v_exp_f32_e32 v171, v33
	v_exp_f32_e32 v172, v34
	v_exp_f32_e32 v173, v35
	v_exp_f32_e32 v174, v36
	v_exp_f32_e32 v175, v37
	v_exp_f32_e32 v176, v38
	v_exp_f32_e32 v158, v52
	v_exp_f32_e32 v177, v39
	v_exp_f32_e32 v159, v53
	v_exp_f32_e32 v178, v40
	v_exp_f32_e32 v160, v54
	v_exp_f32_e32 v179, v41
	v_exp_f32_e32 v48, v48
	v_exp_f32_e32 v49, v49
	v_exp_f32_e32 v50, v50
	v_exp_f32_e32 v51, v51
	v_exp_f32_e32 v161, v55
	v_exp_f32_e32 v180, v42
	v_exp_f32_e32 v162, v56
	v_exp_f32_e32 v181, v43
	ds_read_b64_tr_b16 v[36:37], v195 offset:43136
	ds_read_b64_tr_b16 v[38:39], v195 offset:45824
	v_exp_f32_e32 v163, v57
	v_exp_f32_e32 v182, v44
	v_exp_f32_e32 v164, v58
	v_exp_f32_e32 v183, v45
	v_exp_f32_e32 v165, v59
	v_exp_f32_e32 v184, v46
	v_exp_f32_e32 v166, v60
	v_cvt_pk_bf16_f32 v32, v48, v49
	v_cvt_pk_bf16_f32 v33, v50, v51
	v_cvt_pk_bf16_f32 v34, v158, v159
	v_cvt_pk_bf16_f32 v35, v160, v161
	v_exp_f32_e32 v167, v61
	s_waitcnt lgkmcnt(0)
	v_mfma_f32_32x32x16_bf16 v[16:31], v[36:39], v[32:35], v[16:31]
	v_exp_f32_e32 v168, v62
	v_exp_f32_e32 v169, v63
	v_add_f32_e32 v153, v49, v48
	v_add_f32_e32 v153, v50, v153
	v_add_f32_e32 v153, v51, v153
	v_exp_f32_e32 v185, v47
	ds_read_b64_tr_b16 v[44:45], v195 offset:48512
	ds_read_b64_tr_b16 v[46:47], v195 offset:51200
	ds_read_b64_tr_b16 v[50:51], v195 offset:45888
	ds_read_b64_tr_b16 v[48:49], v195 offset:43200
	v_cvt_pk_bf16_f32 v40, v162, v163
	v_cvt_pk_bf16_f32 v41, v164, v165
	v_cvt_pk_bf16_f32 v42, v166, v167
	v_cvt_pk_bf16_f32 v43, v168, v169
	ds_read_b64_tr_b16 v[52:53], v195 offset:53888
	ds_read_b64_tr_b16 v[54:55], v195 offset:56576
	ds_read_b64_tr_b16 v[58:59], v195 offset:51264
	ds_read_b64_tr_b16 v[56:57], v195 offset:48576
	s_waitcnt lgkmcnt(6)
	v_mfma_f32_32x32x16_bf16 v[16:31], v[44:47], v[40:43], v[16:31]
	v_cvt_pk_bf16_f32 v36, v170, v171
	v_cvt_pk_bf16_f32 v37, v172, v173
	v_cvt_pk_bf16_f32 v38, v174, v175
	v_cvt_pk_bf16_f32 v39, v176, v177
	ds_read_b64_tr_b16 v[44:45], v195 offset:59264
	ds_read_b64_tr_b16 v[46:47], v195 offset:61952
	ds_read_b64_tr_b16 v[62:63], v195 offset:56640
	ds_read_b64_tr_b16 v[60:61], v195 offset:53952
	ds_read_b64_tr_b16 v[156:157], v195 offset:62016
	ds_read_b64_tr_b16 v[154:155], v195 offset:59328
	s_waitcnt lgkmcnt(8)
	v_mfma_f32_32x32x16_bf16 v[16:31], v[52:55], v[36:39], v[16:31]
	v_cvt_pk_bf16_f32 v52, v178, v179
	v_cvt_pk_bf16_f32 v53, v180, v181
	v_cvt_pk_bf16_f32 v54, v182, v183
	v_cvt_pk_bf16_f32 v55, v184, v185
	v_mfma_f32_32x32x16_bf16 v[0:15], v[48:51], v[32:35], v[0:15]
	s_waitcnt lgkmcnt(4)
	v_mfma_f32_32x32x16_bf16 v[16:31], v[44:47], v[52:55], v[16:31]
	v_add_f32_e32 v44, v158, v153
	v_add_f32_e32 v44, v159, v44
	v_add_f32_e32 v44, v160, v44
	v_add_f32_e32 v44, v161, v44
	v_add_f32_e32 v44, v162, v44
	v_add_f32_e32 v44, v163, v44
	v_add_f32_e32 v44, v164, v44
	v_mfma_f32_32x32x16_bf16 v[0:15], v[56:59], v[40:43], v[0:15]
	v_add_f32_e32 v32, v165, v44
	v_add_f32_e32 v32, v166, v32
	v_add_f32_e32 v32, v167, v32
	v_add_f32_e32 v32, v168, v32
	v_add_f32_e32 v32, v169, v32
	v_add_f32_e32 v32, v170, v32
	v_add_f32_e32 v32, v171, v32
	s_waitcnt lgkmcnt(2)
	v_mfma_f32_32x32x16_bf16 v[0:15], v[60:63], v[36:39], v[0:15]
	v_add_f32_e32 v32, v172, v32
	v_add_f32_e32 v32, v173, v32
	v_add_f32_e32 v32, v174, v32
	v_add_f32_e32 v32, v175, v32
	v_add_f32_e32 v32, v176, v32
	v_add_f32_e32 v32, v177, v32
	v_add_f32_e32 v32, v178, v32
	v_add_f32_e32 v32, v179, v32
	s_waitcnt lgkmcnt(0)
	v_mfma_f32_32x32x16_bf16 v[0:15], v[154:157], v[52:55], v[0:15]
	v_add_f32_e32 v32, v180, v32
	v_add_f32_e32 v32, v181, v32
	v_add_f32_e32 v32, v182, v32
	v_add_f32_e32 v32, v183, v32
	v_add_f32_e32 v32, v184, v32
	v_add_f32_e32 v32, v185, v32
	v_add_f32_e32 v151, v151, v32
	ds_read_b128 v[154:157], v194 offset:10816
	ds_read_b128 v[158:161], v194 offset:10848
	s_branch .Lst_bar2
.Lst_skip2:
	s_cmp_ge_i32 s93, s51
	s_cbranch_scc1 .Lst_b2_nost
	s_waitcnt vmcnt(0)
	s_and_saveexec_b64 s[66:67], s[8:9]
	s_cbranch_execz .Lst_b2_s1
	ds_write_b128 v203, v[100:103] offset:21504

.Lst_b2_l2:
	s_or_b64 exec, exec, s[66:67]
.Lst_b2_nold:
	s_waitcnt lgkmcnt(0)
.Lst_bar2:
	s_barrier
	s_add_i32 s69, s69, 3
	s_addk_i32 s68, 0xc0
	s_cmp_lt_u32 s69, s47
	s_cbranch_scc1 .Lst_top
.Lst_exit:
	s_waitcnt lgkmcnt(0)
.Lst_done:
.LBB0_1016:
	v_and_b32_e32 v33, 64, v211
	v_xor_b32_e32 v32, 32, v211
	v_add_u32_e32 v33, 64, v33
	v_cmp_lt_i32_e32 vcc, v32, v33
	s_lshl_b32 s60, s46, 7
	v_lshlrev_b32_e32 v192, 1, v138
	v_cndmask_b32_e32 v32, v211, v32, vcc
	v_lshlrev_b32_e32 v32, 2, v32
	ds_bpermute_b32 v34, v32, v151
	v_lshlrev_b64 v[32:33], 11, v[124:125]
	v_lshl_add_u64 v[32:33], s[48:49], 0, v[32:33]
	v_lshl_add_u64 v[32:33], v[32:33], 0, s[60:61]
	v_lshl_add_u64 v[32:33], v[32:33], 0, v[192:193]
	s_waitcnt lgkmcnt(0)
	v_add_f32_e32 v34, v151, v34
	v_div_scale_f32 v35, s[4:5], v34, v34, 1.0
	v_rcp_f32_e32 v36, v35
	s_mov_b64 s[8:9], 0
	v_fma_f32 v37, -v35, v36, 1.0
	v_fmac_f32_e32 v36, v37, v36
	v_div_scale_f32 v37, vcc, 1.0, v34, 1.0
	v_mul_f32_e32 v38, v37, v36
	v_fma_f32 v39, -v35, v38, v37
	v_fmac_f32_e32 v38, v39, v36
	v_fma_f32 v35, -v35, v38, v37
	v_div_fmas_f32 v35, v35, v36, v38
	v_div_fixup_f32 v34, v35, v34, 1.0
	v_pk_mul_f32 v[16:17], v[16:17], v[34:35] op_sel_hi:[1,0]
	v_pk_mul_f32 v[18:19], v[18:19], v[34:35] op_sel_hi:[1,0]
	v_pk_mul_f32 v[0:1], v[0:1], v[34:35] op_sel_hi:[1,0]
	v_pk_mul_f32 v[2:3], v[2:3], v[34:35] op_sel_hi:[1,0]
	v_cvt_pk_bf16_f32 v16, v16, v17
	v_cvt_pk_bf16_f32 v17, v18, v19
	v_pk_mul_f32 v[18:19], v[20:21], v[34:35] op_sel_hi:[1,0]
	v_pk_mul_f32 v[20:21], v[22:23], v[34:35] op_sel_hi:[1,0]
	v_cvt_pk_bf16_f32 v0, v0, v1
	v_cvt_pk_bf16_f32 v1, v2, v3
	v_pk_mul_f32 v[2:3], v[4:5], v[34:35] op_sel_hi:[1,0]
	v_pk_mul_f32 v[4:5], v[6:7], v[34:35] op_sel_hi:[1,0]
	v_cvt_pk_bf16_f32 v18, v18, v19
	v_cvt_pk_bf16_f32 v19, v20, v21
	v_cvt_pk_bf16_f32 v2, v2, v3
	v_cvt_pk_bf16_f32 v3, v4, v5
	v_permlane32_swap_b32_e32 v16, v18
	v_permlane32_swap_b32_e32 v17, v19
	v_permlane32_swap_b32_e32 v0, v2
	v_permlane32_swap_b32_e32 v1, v3
	global_store_dwordx4 v[32:33], v[16:19], off
	global_store_dwordx4 v[32:33], v[0:3], off offset:64
	v_pk_mul_f32 v[20:21], v[30:31], v[34:35] op_sel_hi:[1,0]
	v_pk_mul_f32 v[16:17], v[24:25], v[34:35] op_sel_hi:[1,0]
	v_pk_mul_f32 v[18:19], v[26:27], v[34:35] op_sel_hi:[1,0]
	v_pk_mul_f32 v[0:1], v[8:9], v[34:35] op_sel_hi:[1,0]
	v_pk_mul_f32 v[2:3], v[10:11], v[34:35] op_sel_hi:[1,0]
	v_cvt_pk_bf16_f32 v16, v16, v17
	v_cvt_pk_bf16_f32 v17, v18, v19
	v_pk_mul_f32 v[18:19], v[28:29], v[34:35] op_sel_hi:[1,0]
	v_cvt_pk_bf16_f32 v0, v0, v1
	v_cvt_pk_bf16_f32 v1, v2, v3
	v_pk_mul_f32 v[2:3], v[12:13], v[34:35] op_sel_hi:[1,0]
	v_pk_mul_f32 v[4:5], v[14:15], v[34:35] op_sel_hi:[1,0]
	v_cvt_pk_bf16_f32 v18, v18, v19
	v_cvt_pk_bf16_f32 v19, v20, v21
	v_cvt_pk_bf16_f32 v2, v2, v3
	v_cvt_pk_bf16_f32 v3, v4, v5
	v_permlane32_swap_b32_e32 v16, v18
	v_permlane32_swap_b32_e32 v17, v19
	v_permlane32_swap_b32_e32 v0, v2
	v_permlane32_swap_b32_e32 v1, v3
	global_store_dwordx4 v[32:33], v[16:19], off offset:32
	global_store_dwordx4 v[32:33], v[0:3], off offset:96
